# scan: K-tile global loads coalesced (16 lanes per 256B row instead of row-per-lane), same LDS image
# speedup vs baseline: 1.0216x; 1.0035x over previous
.LBB0_934:
	s_or_b64 exec, exec, s[10:11]
	s_cmpk_gt_i32 s69, 0x1ff
	s_waitcnt lgkmcnt(0)
	s_barrier
	s_cbranch_scc1 .LBB0_990
	v_lshlrev_b32_e32 v159, 2, v220
	v_or_b32_e32 v157, v87, v148
	v_or_b32_e32 v6, 2, v159
	v_cmp_lt_u32_e64 s[18:19], v157, v6
	v_or_b32_e32 v6, 3, v159
	v_cmp_lt_u32_e64 s[20:21], v157, v6
	v_or_b32_e32 v6, 16, v159
	v_cmp_lt_u32_e64 s[12:13], 63, v146
	v_cmp_ge_u32_e32 vcc, v157, v6
	v_cmp_gt_u32_e64 s[10:11], 64, v146
	s_and_b64 s[44:45], s[12:13], vcc
	v_cmp_le_u32_e32 vcc, v157, v6
	v_or_b32_e32 v6, 18, v159
	s_or_b64 s[46:47], s[10:11], vcc
	v_cmp_lt_u32_e32 vcc, v157, v6
	v_or_b32_e32 v6, 19, v159
	s_or_b64 s[48:49], s[10:11], vcc
	v_cmp_lt_u32_e32 vcc, v157, v6
	s_movk_i32 s1, 0x80
	s_or_b64 s[50:51], s[10:11], vcc
	v_cmp_gt_u32_e32 vcc, s1, v146
	s_movk_i32 s1, 0x7f
	v_or_b32_e32 v6, 32, v159
	v_cmp_lt_u32_e64 s[22:23], s1, v146
	v_cmp_ge_u32_e64 s[24:25], v157, v6
	v_writelane_b32 v253, s66, 19
	s_and_b64 s[52:53], s[22:23], s[24:25]
	v_cmp_le_u32_e64 s[24:25], v157, v6
	v_or_b32_e32 v6, 34, v159
	v_writelane_b32 v253, s67, 20
	s_or_b64 s[54:55], vcc, s[24:25]
	v_cmp_lt_u32_e64 s[24:25], v157, v6
	v_or_b32_e32 v6, 35, v159
	s_or_b64 s[56:57], vcc, s[24:25]
	v_cmp_lt_u32_e64 s[24:25], v157, v6
	s_movk_i32 s1, 0xc0
	v_readlane_b32 s2, v253, 0
	s_or_b64 s[58:59], vcc, s[24:25]
	v_cmp_gt_u32_e32 vcc, s1, v146
	s_movk_i32 s1, 0xbf
	v_or_b32_e32 v6, 48, v159
	v_readlane_b32 s3, v253, 1
	v_cmp_lt_u32_e64 s[24:25], s1, v146
	v_cmp_ge_u32_e64 s[26:27], v157, v6
	s_load_dwordx4 s[40:43], s[2:3], 0x158
	s_and_b64 s[60:61], s[24:25], s[26:27]
	v_cmp_le_u32_e64 s[26:27], v157, v6
	v_or_b32_e32 v6, 50, v159
	s_or_b64 s[62:63], vcc, s[26:27]
	v_cmp_lt_u32_e64 s[26:27], v157, v6
	v_or_b32_e32 v6, 51, v159
	v_lshrrev_b32_e32 v3, 1, v146
	s_or_b64 s[64:65], vcc, s[26:27]
	v_cmp_lt_u32_e64 s[26:27], v157, v6
	v_lshlrev_b32_e32 v122, 4, v220
	v_and_b32_e32 v3, 0x1c0, v3
	s_or_b64 s[66:67], vcc, s[26:27]
	v_add_u32_e32 v3, v122, v3
	v_lshlrev_b32_e32 v4, 3, v147
	s_waitcnt lgkmcnt(0)
	s_add_u32 s82, s42, 0x9440000
	v_and_or_b32 v3, v4, 8, v3
	v_mul_u32_u24_e32 v6, 0x50, v148
	s_addc_u32 s83, s43, 0
	v_lshl_add_u32 v199, v6, 1, v3
	v_lshlrev_b32_e32 v3, 12, v147
	s_add_u32 s84, s42, 0xa440000
	v_lshlrev_b32_e32 v0, 5, v147
	v_lshl_or_b32 v201, v220, 9, v3
	v_lshlrev_b32_e32 v3, 2, v156
	s_addc_u32 s85, s43, 0
	v_lshlrev_b32_e32 v120, 3, v220
	v_lshrrev_b32_e32 v4, 2, v148
	v_or_b32_e32 v206, 0x10e00, v3
	v_or_b32_e32 v207, 0x11000, v3
	v_or_b32_e32 v3, v159, v0
	s_load_dwordx2 s[80:81], s[2:3], 0x30
	s_add_u32 s3, s42, 0xb440000
	s_movk_i32 s0, 0x110
	v_lshlrev_b32_e32 v2, 6, v147
	v_or_b32_e32 v5, v120, v4
	v_and_b32_e32 v4, 12, v155
	v_lshlrev_b32_e32 v124, 7, v3
	v_mov_b32_e32 v3, 0x10f00
	s_addc_u32 s4, s43, 0
	v_mov_b32_e32 v8, 0
	s_nop 0
	v_mul_u32_u24_e32 v197, 0x110, v5
	v_mad_u32_u24 v208, v157, s0, v122
	v_lshl_add_u32 v211, v157, 2, v3
	v_and_or_b32 v212, v156, 48, v3
	v_mad_u32_u24 v3, v5, s0, v2
	v_lshlrev_b32_e32 v5, 1, v4
	s_movk_i32 s0, 0x4400
	s_add_u32 s86, s42, 0xf57c000
	v_add3_u32 v213, v3, v5, s0
	s_addc_u32 s87, s43, 0
	v_lshlrev_b32_e32 v16, 7, v157
	v_mov_b32_e32 v17, v8
	v_mov_b32_e32 v3, v8
	v_and_b32_e32 v1, 0x3c0, v146
	s_add_u32 s5, s42, 0xd440000
	v_lshl_add_u64 v[16:17], s[42:43], 0, v[16:17]
	v_mov_b32_e32 v123, v8
	v_and_b32_e32 v128, 15, v156
	v_lshlrev_b32_e32 v128, 4, v128
	v_mov_b32_e32 v129, 0
	v_lshl_add_u64 v[128:129], s[84:85], 0, v[128:129]
	v_lshl_or_b32 v2, v147, 11, v232
	v_add_u32_e32 v1, v1, v120
	v_mul_u32_u24_e32 v121, 0x110, v148
	v_or_b32_e32 v190, v159, v87
	v_add_u32_e32 v196, v0, v120
	s_addc_u32 s8, s43, 0
	v_lshl_add_u64 v[16:17], v[16:17], 0, v[122:123]
	s_mov_b64 s[0:1], 0xc440000
	v_and_or_b32 v2, v146, 48, v2
	v_add_u32_e32 v9, v196, v0
	v_or_b32_e32 v6, 0x800, v124
	v_mov_b32_e32 v7, v8
	v_or_b32_e32 v10, 0x880, v124
	v_mov_b32_e32 v11, v8
	v_or_b32_e32 v12, 0x900, v124
	v_mov_b32_e32 v13, v8
	v_or_b32_e32 v14, 0x980, v124
	v_mov_b32_e32 v15, v8
	v_lshlrev_b32_e32 v18, 2, v190
	v_lshl_add_u64 v[126:127], v[16:17], 0, s[0:1]
	s_add_u32 s88, s40, 0x4800000
	v_lshl_add_u64 v[2:3], s[42:43], 0, v[2:3]
	s_mov_b64 s[0:1], 0xc442000
	v_add_u32_e32 v1, v1, v121
	v_mbcnt_hi_u32_b32 v222, -1, v145
	v_bitop3_b32 v191, v159, v87, v159 bitop3:3
	v_bitop3_b32 v192, v159, -2, v87 bitop3:0x36
	v_bitop3_b32 v193, v159, -3, v87 bitop3:0x36
	v_bitop3_b32 v194, v159, -4, v87 bitop3:0x36
	v_mul_u32_u24_e32 v198, 0xa0, v148
	v_cmp_ge_u32_e64 s[14:15], v157, v159
	v_cmp_gt_u32_e64 s[16:17], v157, v159
	v_add_u32_e32 v200, 0xa00, v199
	s_mov_b32 s79, 0
	v_cmp_eq_u32_e64 s[26:27], 0, v156
	v_cmp_gt_u32_e64 s[28:29], 2, v156
	v_cmp_gt_u32_e64 s[30:31], 4, v156
	v_cmp_gt_u32_e64 s[34:35], 8, v156
	v_cmp_gt_u32_e64 s[36:37], 16, v156
	v_cmp_gt_u32_e64 s[38:39], 32, v156
	v_or_b32_e32 v202, 0x800, v201
	v_or_b32_e32 v203, 0x880, v201
	v_or_b32_e32 v204, 0x900, v201
	v_or_b32_e32 v205, 0x980, v201
	v_mov_b32_e32 v125, v8
	v_add_u32_e32 v209, 0x10f00, v18
	v_add_u32_e32 v210, 0x11100, v18
	v_lshl_add_u64 v[130:131], s[82:83], 0, v[122:123]
	s_addc_u32 s89, s41, 0
	v_add_u32_e32 v123, 0x11000, v18
	v_lshl_add_u64 v[132:133], v[2:3], 0, s[0:1]
	v_sub_u32_e32 v214, 0xffffffbf, v157
	v_lshrrev_b32_e32 v215, 4, v156
	v_lshl_add_u32 v215, v147, 2, v215
	v_and_b32_e32 v216, 15, v156
	v_lshlrev_b32_e32 v216, 4, v216
	v_mul_u32_u24_e32 v195, 0x110, v215
	v_add_u32_e32 v195, v195, v216
	v_xor_b32_e32 v216, 0xffffffbf, v215
	v_or_b32_e32 v215, 64, v215
	v_lshlrev_b32_e32 v134, 1, v0
	v_mov_b32_e32 v135, v8
	v_lshlrev_b32_e32 v136, 1, v120
	v_mov_b32_e32 v137, v8
	v_lshlrev_b32_e32 v138, 1, v148
	v_mov_b32_e32 v139, v8
	s_mov_b32 s9, 0x5040100
	v_lshlrev_b32_e32 v217, 1, v4
	v_mov_b32_e32 v218, 0x10ffc
	v_lshlrev_b64 v[140:141], 2, v[6:7]
	v_lshlrev_b64 v[142:143], 2, v[10:11]
	v_lshlrev_b64 v[160:161], 2, v[12:13]
	v_lshlrev_b64 v[162:163], 2, v[14:15]
	v_add_u32_e32 v219, 0x8800, v1
	v_add_u32_e32 v221, 0x9800, v1
	v_and_b32_e32 v223, 64, v222
	v_add_u32_e32 v224, -1, v222
	v_add_u32_e32 v225, -2, v222
	v_add_u32_e32 v226, -4, v222
	v_add_u32_e32 v227, -8, v222
	v_add_u32_e32 v228, -16, v222
	v_subrev_u32_e32 v229, 32, v222
	v_add_u32_e32 v235, v9, v121
	s_mov_b32 s68, s69
	s_branch .LBB0_937

.LBB0_946:
	s_waitcnt vmcnt(14)
	v_cvt_pk_bf16_f32 v0, v16, v17
	s_waitcnt vmcnt(12)
	v_cvt_pk_bf16_f32 v1, v18, v19
	s_waitcnt vmcnt(6)
	v_cvt_pk_bf16_f32 v4, v20, v21
	s_waitcnt vmcnt(4)
	v_cvt_pk_bf16_f32 v5, v22, v23
	s_waitcnt lgkmcnt(0)
	s_barrier
	v_cvt_pk_bf16_f32 v2, v12, v13
	v_cvt_pk_bf16_f32 v3, v14, v15
	ds_write2_b64 v219, v[0:1], v[4:5] offset1:4
	s_waitcnt vmcnt(2)
	v_cvt_pk_bf16_f32 v0, v24, v25
	s_waitcnt vmcnt(0)
	v_cvt_pk_bf16_f32 v1, v26, v27
	ds_write2_b64 v221, v[2:3], v[0:1] offset0:32 offset1:36
	s_cmp_eq_u32 s0, 0
	v_subrev_u32_e32 v9, 64, v215
	v_not_b32_e32 v0, v9
	s_cselect_b64 vcc, -1, 0
	v_add_u32_e32 v0, s6, v0
	v_cndmask_b32_e32 v0, v0, v9, vcc
	v_add_u32_e32 v0, s33, v0
	v_ashrrev_i32_e32 v1, 31, v0
	v_lshlrev_b64 v[0:1], 11, v[0:1]
	v_lshl_add_u64 v[0:1], v[128:129], 0, v[0:1]
	s_lshl_b32 s78, s94, 8
	v_lshl_add_u64 v[10:11], v[0:1], 0, s[78:79]
	v_mov_b32_e32 v36, 0xffff8000
	v_mov_b32_e32 v37, 0x8000
	v_cndmask_b32_e32 v36, v36, v37, vcc
	v_mov_b32_e32 v37, 0
	v_cndmask_b32_e32 v37, -1, v37, vcc
	global_load_dwordx4 v[32:35], v[10:11], off
	v_lshl_add_u64 v[10:11], v[10:11], 0, v[36:37]
	global_load_dwordx4 v[28:31], v[10:11], off
	v_lshl_add_u64 v[10:11], v[10:11], 0, v[36:37]
	global_load_dwordx4 v[4:7], v[10:11], off
	v_lshl_add_u64 v[10:11], v[10:11], 0, v[36:37]
	global_load_dwordx4 v[0:3], v[10:11], off
	s_and_saveexec_b64 s[40:41], s[12:13]
	s_xor_b64 s[40:41], exec, s[40:41]
	s_lshl_b32 s72, s0, 3
	s_or_saveexec_b64 s[40:41], s[40:41]
	v_mov_b32_e32 v236, 0
	v_mov_b32_e32 v164, s72
	v_mov_b32_e32 v237, 0
	s_xor_b64 exec, exec, s[40:41]
	s_cbranch_execz .LBB0_950
	v_not_b32_e32 v9, v146
	v_add_u32_e32 v9, s6, v9
	v_cndmask_b32_e32 v9, v9, v146, vcc
	v_add_u32_e32 v10, s33, v9
	v_ashrrev_i32_e32 v11, 31, v10
	v_lshlrev_b64 v[10:11], 7, v[10:11]
	v_lshl_add_u64 v[10:11], s[86:87], 0, v[10:11]
	s_lshl_b32 s78, s0, 5
	v_lshl_add_u64 v[10:11], v[10:11], 0, s[78:79]
	s_lshl_b32 s78, s94, 2
	v_lshl_add_u64 v[10:11], v[10:11], 0, s[78:79]
	global_load_dword v237, v[10:11], off offset:64
	global_load_dword v236, v[10:11], off
	s_lshl_b32 s72, s0, 3
	v_mov_b32_e32 v164, s72
.LBB0_950:
	s_or_b64 exec, exec, s[40:41]
	v_not_b32_e32 v9, v157
	v_add_u32_e32 v9, s6, v9
	v_cndmask_b32_e32 v9, v9, v157, vcc
	v_add_u32_e32 v10, s33, v9
	v_ashrrev_i32_e32 v11, 31, v10
	s_lshl_b32 s40, s94, 7
	v_lshlrev_b64 v[10:11], 11, v[10:11]
	v_lshl_add_u64 v[10:11], s[82:83], 0, v[10:11]
	s_lshl_b32 s78, s40, 1
	v_lshl_add_u64 v[10:11], v[10:11], 0, s[78:79]
	v_lshl_add_u64 v[10:11], v[10:11], 0, v[136:137]
	v_or_b32_e32 v9, s94, v164
	global_load_dwordx4 v[88:91], v[10:11], off
	global_load_dwordx4 v[84:87], v[10:11], off offset:64
	global_load_dwordx4 v[80:83], v[10:11], off offset:128
	global_load_dwordx4 v[76:79], v[10:11], off offset:192
	v_lshl_add_u32 v10, v9, 7, s7
	v_ashrrev_i32_e32 v11, 31, v10
	v_lshlrev_b64 v[36:37], 13, v[10:11]
	s_add_u32 s7, s3, s78
	v_add_u32_e32 v9, s6, v191
	v_lshl_add_u64 v[10:11], v[126:127], 0, v[36:37]
	s_addc_u32 s41, s4, 0
	s_lshl_b32 s40, s2, 6
	v_cndmask_b32_e32 v9, v9, v190, vcc
	global_load_dwordx4 v[56:59], v[10:11], off
	global_load_dwordx4 v[52:55], v[10:11], off offset:64
	s_add_u32 s40, s7, s40
	v_add_u32_e32 v10, s33, v9
	s_addc_u32 s41, s41, 0
	v_ashrrev_i32_e32 v11, 31, v10
	v_lshl_add_u64 v[174:175], s[40:41], 0, v[138:139]
	v_lshlrev_b64 v[10:11], 11, v[10:11]
	v_lshl_add_u64 v[10:11], v[174:175], 0, v[10:11]
	global_load_ushort v38, v[10:11], off
	global_load_ushort v9, v[10:11], off offset:32
	v_add_u32_e32 v10, s6, v192
	v_or_b32_e32 v11, 1, v190
	v_cndmask_b32_e32 v10, v10, v11, vcc
	v_add_u32_e32 v10, s33, v10
	v_ashrrev_i32_e32 v11, 31, v10
	v_lshlrev_b64 v[10:11], 11, v[10:11]
	v_lshl_add_u64 v[10:11], v[174:175], 0, v[10:11]
	global_load_ushort v40, v[10:11], off
	global_load_ushort v39, v[10:11], off offset:32
	v_add_u32_e32 v10, s6, v193
	v_or_b32_e32 v11, 2, v190
	v_cndmask_b32_e32 v10, v10, v11, vcc
	v_add_u32_e32 v10, s33, v10
	v_ashrrev_i32_e32 v11, 31, v10
	v_lshlrev_b64 v[10:11], 11, v[10:11]
	v_lshl_add_u64 v[10:11], v[174:175], 0, v[10:11]
	global_load_ushort v42, v[10:11], off
	global_load_ushort v41, v[10:11], off offset:32
	v_add_u32_e32 v10, s6, v194
	v_or_b32_e32 v11, 3, v190
	v_cndmask_b32_e32 v10, v10, v11, vcc
	v_add_u32_e32 v10, s33, v10
	v_ashrrev_i32_e32 v11, 31, v10
	v_lshlrev_b64 v[10:11], 11, v[10:11]
	v_lshl_add_u64 v[10:11], v[174:175], 0, v[10:11]
	global_load_ushort v44, v[10:11], off
	global_load_ushort v43, v[10:11], off offset:32
	s_waitcnt vmcnt(14)
	ds_write_b128 v195, v[32:35]
	ds_write_b128 v195, v[28:31] offset:4352
	ds_write_b128 v195, v[4:7] offset:8704
	ds_write_b128 v195, v[0:3] offset:13056
	s_and_saveexec_b64 s[92:93], s[10:11]
	s_cbranch_execz .LBB0_952
	v_cmp_lt_i32_e64 s[40:41], v224, v223
	s_nop 1
	v_cndmask_b32_e64 v0, v224, v222, s[40:41]
	v_lshlrev_b32_e32 v0, 2, v0
	ds_bpermute_b32 v0, v0, v237
	v_cmp_lt_i32_e64 s[40:41], v225, v223
	s_waitcnt lgkmcnt(0)
	v_add_f32_e32 v0, v237, v0
	v_cndmask_b32_e64 v1, v225, v222, s[40:41]
	v_cndmask_b32_e64 v0, v0, v237, s[26:27]
	v_lshlrev_b32_e32 v1, 2, v1
	ds_bpermute_b32 v1, v1, v0
	v_cmp_lt_i32_e64 s[40:41], v226, v223
	s_waitcnt lgkmcnt(0)
	v_add_f32_e32 v1, v0, v1
	v_cndmask_b32_e64 v0, v1, v0, s[28:29]
	v_cndmask_b32_e64 v1, v226, v222, s[40:41]
	v_lshlrev_b32_e32 v1, 2, v1
	ds_bpermute_b32 v1, v1, v0
	v_cmp_lt_i32_e64 s[40:41], v227, v223
	s_waitcnt lgkmcnt(0)
	v_add_f32_e32 v1, v0, v1
	v_cndmask_b32_e64 v0, v1, v0, s[30:31]
	v_cndmask_b32_e64 v1, v227, v222, s[40:41]
	v_lshlrev_b32_e32 v1, 2, v1
	ds_bpermute_b32 v1, v1, v0
	v_cmp_lt_i32_e64 s[40:41], v228, v223
	s_waitcnt lgkmcnt(0)
	v_add_f32_e32 v1, v0, v1
	v_cndmask_b32_e64 v0, v1, v0, s[34:35]
	v_cndmask_b32_e64 v1, v228, v222, s[40:41]
	v_lshlrev_b32_e32 v1, 2, v1
	ds_bpermute_b32 v1, v1, v0
	v_cmp_lt_i32_e64 s[40:41], v229, v223
	s_waitcnt lgkmcnt(0)
	v_add_f32_e32 v1, v0, v1
	v_cndmask_b32_e64 v0, v1, v0, s[36:37]
	v_cndmask_b32_e64 v1, v229, v222, s[40:41]
	v_lshlrev_b32_e32 v1, 2, v1
	ds_bpermute_b32 v1, v1, v0
	s_waitcnt lgkmcnt(0)
	v_add_f32_e32 v1, v0, v1
	v_cndmask_b32_e64 v0, v1, v0, s[38:39]
	ds_write_b32 v206, v0
	ds_write_b32 v207, v236

.LBB0_953:
	v_add_u32_e32 v3, s2, v215
	v_add_u32_e32 v5, s7, v216
	v_cndmask_b32_e32 v3, v5, v3, vcc
	v_add_u32_e32 v6, s33, v3
	v_ashrrev_i32_e32 v7, 31, v6
	v_lshlrev_b64 v[6:7], 11, v[6:7]
	v_lshl_add_u64 v[6:7], v[176:177], 0, v[6:7]
	s_waitcnt lgkmcnt(0)
	s_barrier
	v_mov_b32_e32 v92, 0xffff8000
	v_mov_b32_e32 v93, 0x8000
	v_cndmask_b32_e32 v92, v92, v93, vcc
	v_mov_b32_e32 v93, 0
	v_cndmask_b32_e32 v93, -1, v93, vcc
	global_load_dwordx4 v[72:75], v[6:7], off
	v_lshl_add_u64 v[6:7], v[6:7], 0, v[92:93]
	global_load_dwordx4 v[68:71], v[6:7], off
	v_lshl_add_u64 v[6:7], v[6:7], 0, v[92:93]
	global_load_dwordx4 v[64:67], v[6:7], off
	v_lshl_add_u64 v[6:7], v[6:7], 0, v[92:93]
	global_load_dwordx4 v[60:63], v[6:7], off
	s_and_saveexec_b64 s[40:41], s[10:11]
	s_cbranch_execz .LBB0_955
	v_add_u32_e32 v3, 64, v146
	v_sub_u32_e32 v5, 0xffffffbf, v146
	v_add_u32_e32 v3, s2, v3
	v_add_u32_e32 v5, s7, v5
	v_cndmask_b32_e32 v3, v5, v3, vcc
	v_add_u32_e32 v6, s33, v3
	v_ashrrev_i32_e32 v7, 31, v6
	v_lshlrev_b64 v[6:7], 7, v[6:7]
	v_lshl_add_u64 v[6:7], v[180:181], 0, v[6:7]
	global_load_dword v237, v[6:7], off offset:64
	global_load_dword v236, v[6:7], off

.LBB0_969:
	s_or_b64 exec, exec, s[40:41]
	s_waitcnt lgkmcnt(1)
	v_sub_f32_e32 v76, v249, v76
	v_sub_f32_e32 v1, v249, v2
	v_sub_f32_e32 v2, v249, v3
	v_sub_f32_e32 v3, v249, v250
	v_sub_f32_e32 v5, v249, v6
	v_sub_f32_e32 v79, v249, v188
	v_mul_f32_e32 v76, 0x3fb8aa3b, v76
	v_sub_f32_e32 v77, v249, v77
	v_mul_f32_e32 v1, 0x3fb8aa3b, v1
	v_mul_f32_e32 v2, 0x3fb8aa3b, v2
	v_mul_f32_e32 v3, 0x3fb8aa3b, v3
	v_mul_f32_e32 v5, 0x3fb8aa3b, v5
	v_mul_f32_e32 v79, 0x3fb8aa3b, v79
	v_exp_f32_e32 v76, v76
	v_mul_f32_e32 v77, 0x3fb8aa3b, v77
	s_waitcnt lgkmcnt(0)
	v_sub_f32_e32 v78, v249, v78
	v_exp_f32_e32 v1, v1
	v_exp_f32_e32 v2, v2
	v_exp_f32_e32 v3, v3
	v_exp_f32_e32 v5, v5
	v_exp_f32_e32 v79, v79
	v_exp_f32_e32 v77, v77
	v_mul_f32_e32 v78, 0x3fb8aa3b, v78
	v_exp_f32_e32 v78, v78
	v_sub_f32_e32 v80, v249, v189
	v_mul_f32_e32 v80, 0x3fb8aa3b, v80
	v_sub_f32_e32 v81, v249, v252
	v_mul_f32_e32 v76, v117, v76
	v_mul_f32_e32 v1, v105, v1
	v_mul_f32_e32 v2, v106, v2
	v_mul_f32_e32 v3, v107, v3
	v_mul_f32_e32 v5, v109, v5
	v_exp_f32_e32 v80, v80
	v_mul_f32_e32 v79, v113, v79
	v_mul_f32_e32 v81, 0x3fb8aa3b, v81
	v_cndmask_b32_e64 v106, v76, 0, s[62:63]
	v_mul_f32_e32 v76, v118, v77
	v_cndmask_b32_e64 v1, 0, v1, s[16:17]
	v_cndmask_b32_e64 v2, v2, 0, s[18:19]
	v_cndmask_b32_e64 v3, v3, 0, s[20:21]
	v_cndmask_b32_e64 v5, v5, 0, s[46:47]
	v_cndmask_b32_e64 v79, v79, 0, s[54:55]
	v_exp_f32_e32 v81, v81
	v_cndmask_b32_e64 v107, v76, 0, s[64:65]
	v_mul_f32_e32 v76, v119, v78
	v_add_u32_e32 v86, v122, v198
	v_cndmask_b32_e64 v109, v76, 0, s[66:67]
	v_cvt_pk_bf16_f32 v0, v0, v1
	v_cvt_pk_bf16_f32 v1, v2, v3
	v_cvt_pk_bf16_f32 v2, v4, v5
	v_cvt_pk_bf16_f32 v4, v108, v79
	s_barrier
	ds_read_b128 v[76:79], v86 offset:43520
	v_mul_f32_e32 v80, v114, v80
	v_cndmask_b32_e64 v87, v80, 0, s[56:57]
	v_mul_f32_e32 v80, v115, v81
	v_cndmask_b32_e64 v105, v80, 0, s[58:59]
	ds_read_b128 v[80:83], v86 offset:43584
	s_waitcnt lgkmcnt(1)
	v_mfma_f32_16x16x32_bf16 v[76:79], v[56:59], v[76:79], 0
	v_sub_f32_e32 v6, v249, v7
	v_sub_f32_e32 v7, v249, v251
	v_mul_f32_e32 v6, 0x3fb8aa3b, v6
	s_waitcnt lgkmcnt(0)
	v_mfma_f32_16x16x32_bf16 v[76:79], v[52:55], v[80:83], v[76:79]
	v_mul_f32_e32 v7, 0x3fb8aa3b, v7
	v_exp_f32_e32 v6, v6
	v_exp_f32_e32 v7, v7
	v_sub_f32_e32 v5, v248, v100
	v_mul_f32_e32 v5, 0x3fb8aa3b, v5
	s_nop 2
	v_cvt_pk_bf16_f32 v80, v76, v77
	v_cvt_pk_bf16_f32 v81, v78, v79
	ds_write_b64 v199, v[80:81] offset:48640
	v_mul_f32_e32 v6, v110, v6
	v_mul_f32_e32 v7, v111, v7
	ds_read_b128 v[80:83], v86 offset:46080
	v_cndmask_b32_e64 v6, v6, 0, s[48:49]
	v_cndmask_b32_e64 v7, v7, 0, s[50:51]
	v_cvt_pk_bf16_f32 v3, v6, v7
	v_exp_f32_e32 v6, v5
	v_sub_f32_e32 v5, v248, v101
	v_mul_f32_e32 v5, 0x3fb8aa3b, v5
	v_exp_f32_e32 v7, v5
	v_sub_f32_e32 v5, v248, v102
	ds_read_b128 v[88:91], v86 offset:46144
	v_mul_f32_e32 v5, 0x3fb8aa3b, v5
	s_waitcnt lgkmcnt(1)
	v_mfma_f32_16x16x32_bf16 v[56:59], v[56:59], v[80:83], 0
	v_exp_f32_e32 v84, v5
	v_sub_f32_e32 v5, v248, v103
	v_mul_f32_e32 v5, 0x3fb8aa3b, v5
	v_exp_f32_e32 v85, v5
	s_waitcnt lgkmcnt(0)
	v_mfma_f32_16x16x32_bf16 v[52:55], v[52:55], v[88:91], v[56:59]
	v_mul_f32_e64 v76, v6, v76
	v_mul_f32_e64 v77, v7, v77
	v_cvt_pk_bf16_f32 v5, v87, v105
	v_pk_mul_f32 v[78:79], v[84:85], v[78:79]
	v_cvt_pk_bf16_f32 v76, v76, v77
	v_cvt_pk_bf16_f32 v77, v78, v79
	s_nop 1
	v_cvt_pk_bf16_f32 v56, v52, v53
	v_cvt_pk_bf16_f32 v57, v54, v55
	v_pk_mul_f32 v[6:7], v[6:7], v[52:53]
	v_pk_mul_f32 v[52:53], v[84:85], v[54:55]
	ds_write_b64 v165, v[76:77] offset:53760
	v_cvt_pk_bf16_f32 v6, v6, v7
	v_cvt_pk_bf16_f32 v7, v52, v53
	ds_write_b64 v200, v[56:57] offset:48640
	ds_write_b64 v165, v[6:7] offset:56320
	s_waitcnt lgkmcnt(0)
	s_barrier
	ds_read_b128 v[52:55], v86 offset:48640
	v_cvt_pk_bf16_f32 v6, v104, v106
	v_cvt_pk_bf16_f32 v7, v107, v109
	ds_read_b128 v[56:59], v86 offset:48704
	s_waitcnt lgkmcnt(1)
	v_mfma_f32_16x16x32_bf16 v[52:55], v[0:3], v[52:55], 0
	v_add_u32_e32 v76, -1, v247
	v_cndmask_b32_e32 v76, v76, v246, vcc
	v_add_u32_e32 v76, s33, v76
	s_waitcnt lgkmcnt(0)
	v_mfma_f32_16x16x32_bf16 v[52:55], v[4:7], v[56:59], v[52:55]
	v_ashrrev_i32_e32 v77, 31, v76
	v_lshlrev_b64 v[56:57], 11, v[76:77]
	v_lshl_add_u64 v[76:77], v[10:11], 0, v[56:57]
	v_xad_u32 v56, v246, -2, s6
	v_add_u32_e32 v87, 0x9800, v235
	s_nop 2
	v_fma_f32 v52, v96, v184, v52
	v_cvt_pk_bf16_f32 v52, v52, s0
	global_store_short v[76:77], v52, off
	v_add_u32_e32 v52, 1, v246
	v_cndmask_b32_e32 v52, v56, v52, vcc
	v_add_u32_e32 v52, s33, v52
	v_fma_f32 v53, v97, v185, v53
	v_cvt_pk_bf16_f32 v56, v53, s0
	v_ashrrev_i32_e32 v53, 31, v52
	v_lshlrev_b64 v[52:53], 11, v[52:53]
	v_lshl_add_u64 v[78:79], v[10:11], 0, v[52:53]
	v_add_u32_e32 v52, 2, v246
	v_xad_u32 v53, v246, -3, s6
	v_cndmask_b32_e32 v52, v53, v52, vcc
	v_add_u32_e32 v52, s33, v52
	v_fma_f32 v53, v98, v186, v54
	global_store_short v[78:79], v56, off
	v_cvt_pk_bf16_f32 v54, v53, s0
	v_ashrrev_i32_e32 v53, 31, v52
	ds_read_b128 v[56:59], v86 offset:51200
	v_lshlrev_b64 v[52:53], 11, v[52:53]
	v_lshl_add_u64 v[80:81], v[10:11], 0, v[52:53]
	v_add_u32_e32 v52, 3, v246
	v_xad_u32 v53, v246, -4, s6
	v_cndmask_b32_e32 v52, v53, v52, vcc
	v_fmac_f32_e32 v55, v99, v187
	global_store_short v[80:81], v54, off
	v_add_u32_e32 v82, s33, v52
	v_cvt_pk_bf16_f32 v84, v55, s0
	ds_read_b128 v[52:55], v86 offset:51264
	s_waitcnt lgkmcnt(1)
	v_mfma_f32_16x16x32_bf16 v[0:3], v[0:3], v[56:59], 0
	v_ashrrev_i32_e32 v83, 31, v82
	v_lshlrev_b64 v[56:57], 11, v[82:83]
	v_lshl_add_u64 v[56:57], v[10:11], 0, v[56:57]
	s_waitcnt lgkmcnt(0)
	v_mfma_f32_16x16x32_bf16 v[0:3], v[4:7], v[52:55], v[0:3]
	global_store_short v[56:57], v84, off
	s_nop 6
	v_fma_f32 v0, v92, v184, v0
	v_cvt_pk_bf16_f32 v0, v0, s0
	global_store_short v[76:77], v0, off offset:32
	v_fma_f32 v0, v93, v185, v1
	v_cvt_pk_bf16_f32 v0, v0, s0
	global_store_short v[78:79], v0, off offset:32
	v_fma_f32 v0, v94, v186, v2
	v_cvt_pk_bf16_f32 v0, v0, s0
	v_fmac_f32_e32 v3, v95, v187
	global_store_short v[80:81], v0, off offset:32
	v_cvt_pk_bf16_f32 v0, v3, s0
	global_store_short v[56:57], v0, off offset:32
	v_mul_f32_e32 v0, 0x3fb8aa3b, v248
	v_exp_f32_e32 v84, v0
	v_add_u32_e32 v0, s72, v197
	v_add3_u32 v76, v0, v134, v217
	ds_read_b64_tr_b16 v[56:57], v76
	ds_read_b64_tr_b16 v[58:59], v76 offset:1088
	ds_read_b64_tr_b16 v[52:53], v76 offset:8704
	ds_read_b64_tr_b16 v[54:55], v76 offset:9792
	ds_read_b64_tr_b16 v[4:5], v76 offset:32
	ds_read_b64_tr_b16 v[6:7], v76 offset:1120
	ds_read_b64_tr_b16 v[0:1], v76 offset:8736
	ds_read_b64_tr_b16 v[2:3], v76 offset:9824
	s_waitcnt lgkmcnt(0)
	ds_read_b128 v[76:79], v86 offset:53760
	v_pk_mul_f32 v[18:19], v[18:19], v[84:85] op_sel_hi:[1,0]
	v_pk_mul_f32 v[16:17], v[16:17], v[84:85] op_sel_hi:[1,0]
	ds_read_b128 v[80:83], v86 offset:53824
	v_pk_mul_f32 v[22:23], v[22:23], v[84:85] op_sel_hi:[1,0]
	s_waitcnt lgkmcnt(1)
	v_mfma_f32_16x16x32_bf16 v[16:19], v[56:59], v[76:79], v[16:19]
	v_mul_f32_e64 v20, v20, v84
	v_mul_f32_e64 v21, v21, v84
	v_pk_mul_f32 v[14:15], v[14:15], v[84:85] op_sel_hi:[1,0]
	v_pk_mul_f32 v[12:13], v[12:13], v[84:85] op_sel_hi:[1,0]
	s_waitcnt lgkmcnt(0)
	v_mfma_f32_16x16x32_bf16 v[16:19], v[52:55], v[80:83], v[16:19]
	v_mul_f32_e64 v26, v26, v84
	v_mul_f32_e64 v27, v27, v84
	v_pk_mul_f32 v[24:25], v[24:25], v[84:85] op_sel_hi:[1,0]
	v_mfma_f32_16x16x32_bf16 v[20:23], v[4:7], v[76:79], v[20:23]
	v_mfma_f32_16x16x32_bf16 v[20:23], v[0:3], v[80:83], v[20:23]
	s_nop 2
	v_cvt_pk_bf16_f32 v88, v16, v17
	v_cvt_pk_bf16_f32 v89, v18, v19
	ds_write_b64 v235, v[88:89] offset:34816
	ds_read_b128 v[88:91], v86 offset:56320
	ds_read_b128 v[92:95], v86 offset:56384
	s_waitcnt lgkmcnt(1)
	v_mfma_f32_16x16x32_bf16 v[12:15], v[56:59], v[88:91], v[12:15]
	v_mfma_f32_16x16x32_bf16 v[4:7], v[4:7], v[88:91], v[24:27]
	s_nop 2
	v_cvt_pk_bf16_f32 v24, v20, v21
	v_cvt_pk_bf16_f32 v25, v22, v23
	s_waitcnt lgkmcnt(0)
	v_mfma_f32_16x16x32_bf16 v[12:15], v[52:55], v[92:95], v[12:15]
	ds_write_b64 v235, v[24:25] offset:34848
	v_mfma_f32_16x16x32_bf16 v[24:27], v[0:3], v[92:95], v[4:7]
	s_nop 5
	v_cvt_pk_bf16_f32 v52, v12, v13
	v_cvt_pk_bf16_f32 v53, v14, v15
	v_cvt_pk_bf16_f32 v0, v24, v25
	v_cvt_pk_bf16_f32 v1, v26, v27
	ds_write2_b64 v87, v[52:53], v[0:1] offset0:32 offset1:36
	s_setprio 0
	s_and_b32 s72, s0, 1
	s_mul_i32 s40, s72, 0x4400
	v_add_u32_e32 v0, s40, v195
	s_waitcnt vmcnt(22)
	ds_write_b128 v0, v[72:75]
	ds_write_b128 v0, v[68:71] offset:4352
	ds_write_b128 v0, v[64:67] offset:8704
	ds_write_b128 v0, v[60:63] offset:13056
	s_and_saveexec_b64 s[92:93], s[10:11]
	s_cbranch_execz .LBB0_971
	v_cmp_lt_i32_e64 s[40:41], v224, v223
	s_nop 1
	v_cndmask_b32_e64 v0, v224, v222, s[40:41]
	v_lshlrev_b32_e32 v0, 2, v0
	ds_bpermute_b32 v0, v0, v237
	v_cmp_lt_i32_e64 s[40:41], v225, v223
	s_waitcnt lgkmcnt(0)
	v_add_f32_e32 v0, v237, v0
	v_cndmask_b32_e64 v1, v225, v222, s[40:41]
	v_cndmask_b32_e64 v0, v0, v237, s[26:27]
	v_lshlrev_b32_e32 v1, 2, v1
	ds_bpermute_b32 v1, v1, v0
	v_cmp_lt_i32_e64 s[40:41], v226, v223
	s_waitcnt lgkmcnt(0)
	v_add_f32_e32 v1, v0, v1
	v_cndmask_b32_e64 v0, v1, v0, s[28:29]
	v_cndmask_b32_e64 v1, v226, v222, s[40:41]
	v_lshlrev_b32_e32 v1, 2, v1
	ds_bpermute_b32 v1, v1, v0
	v_cmp_lt_i32_e64 s[40:41], v227, v223
	s_waitcnt lgkmcnt(0)
	v_add_f32_e32 v1, v0, v1
	v_cndmask_b32_e64 v0, v1, v0, s[30:31]
	v_cndmask_b32_e64 v1, v227, v222, s[40:41]
	v_lshlrev_b32_e32 v1, 2, v1
	ds_bpermute_b32 v1, v1, v0
	v_cmp_lt_i32_e64 s[40:41], v228, v223
	s_waitcnt lgkmcnt(0)
	v_add_f32_e32 v1, v0, v1
	v_cndmask_b32_e64 v0, v1, v0, s[34:35]
	v_cndmask_b32_e64 v1, v228, v222, s[40:41]
	v_lshlrev_b32_e32 v1, 2, v1
	ds_bpermute_b32 v1, v1, v0
	v_cmp_lt_i32_e64 s[40:41], v229, v223
	s_waitcnt lgkmcnt(0)
	v_add_f32_e32 v1, v0, v1
	v_cndmask_b32_e64 v0, v1, v0, s[36:37]
	v_cndmask_b32_e64 v1, v229, v222, s[40:41]
	v_lshlrev_b32_e32 v1, 2, v1
	ds_bpermute_b32 v1, v1, v0
	s_waitcnt lgkmcnt(0)
	v_add_f32_e32 v1, v0, v1
	v_cndmask_b32_e64 v0, v1, v0, s[38:39]
	v_lshl_or_b32 v1, s72, 8, v155
	v_add_u32_e32 v2, 0x10e00, v1
	ds_write_b32 v2, v0
	v_or_b32_e32 v0, 0x11000, v1
	ds_write_b32 v0, v236
